# c27 + h3 output section: the 7 remaining out-norm gain vectors loaded together instead of one at a time behind vmcnt(0)
# speedup vs baseline: 1.0106x; 1.0046x over previous
; #define MFMA16(a, b, c) __builtin_amdgcn_mfma_f32_16x16x32_bf16((a), (b), (c), 0, 0, 0)
; __device__ __forceinline__ void h3_unit(int j, const bf16_t* qe, const bf16_t* intra, const bf16_t* Ub, const bf16_t* hg, const float* gn, bf16_t* out) {
;     ...
;         const int combo = 2 * wid + cc, head = combo >> 2, tb = combo & 3, u = (b * 4 + head) * 64 + c;
;         const size_t rbase = (size_t)(t0 + 16 * tb + l15) * 512 + head * 128;
;         bf16x8 x[4];
; #pragma unroll
;         for (int ks = 0; ks < 4; ++ks) x[ks] = __builtin_nontemporal_load((const bf16x8*)(qe + rbase + 8 * l4 + 32 * ks));
;         u32x2 iv[8], gv[8];
; #pragma unroll
;         for (int vb = 0; vb < 8; ++vb) { iv[vb] = __builtin_nontemporal_load((const u32x2*)(intra + rbase + 16 * vb + 4 * l4)); gv[vb] = __builtin_nontemporal_load((const u32x2*)(hg + rbase + 16 * vb + 4 * l4)); }
;         const bf16_t* ub = Ub + (size_t)u * 16384 + l15 * 128 + 8 * l4;
;         f32x4 acc[8];
; #pragma unroll
;         for (int vb = 0; vb < 8; ++vb) { acc[vb] = (f32x4){0.f, 0.f, 0.f, 0.f};
; #pragma unroll
;             for (int ks = 0; ks < 4; ++ks) { const bf16x8 y = *(const bf16x8*)(ub + vb * 2048 + 32 * ks); acc[vb] = MFMA16(y, x[ks], acc[vb]); } }
.LBB0_836:
	s_or_b32 s33, s33, s29
	v_lshl_or_b32 v136, s33, 4, v188
	v_ashrrev_i32_e32 v137, 31, v136
	v_lshlrev_b64 v[24:25], 9, v[136:137]
	v_lshl_add_u64 v[24:25], v[24:25], 0, s[78:79]
	v_lshlrev_b64 v[182:183], 1, v[24:25]
	v_lshl_add_u64 v[222:223], v[64:65], 0, v[182:183]
	global_load_dwordx4 v[8:11], v[76:77], off
	global_load_dwordx4 v[36:39], v[76:77], off offset:64
	global_load_dwordx4 v[40:43], v[76:77], off offset:128
	global_load_dwordx4 v[32:35], v[76:77], off offset:192
	global_load_dwordx4 v[28:31], v[78:79], off
	global_load_dwordx4 v[44:47], v[80:81], off
	global_load_dwordx4 v[48:51], v[82:83], off
	global_load_dwordx4 v[0:3], v[84:85], off
	global_load_dwordx4 v[52:55], v[86:87], off
	global_load_dwordx4 v[56:59], v[88:89], off
	global_load_dwordx4 v[170:173], v[90:91], off
	global_load_dwordx4 v[4:7], v[92:93], off
	global_load_dwordx4 v[60:63], v[94:95], off
	global_load_dwordx4 v[138:141], v[96:97], off
	global_load_dwordx4 v[174:177], v[98:99], off
	global_load_dwordx4 v[12:15], v[100:101], off
	global_load_dwordx4 v[142:145], v[102:103], off
	global_load_dwordx4 v[154:157], v[104:105], off
	global_load_dwordx4 v[190:193], v[106:107], off
	global_load_dwordx4 v[16:19], v[108:109], off
	global_load_dwordx4 v[146:149], v[110:111], off
	global_load_dwordx4 v[158:161], v[112:113], off
	global_load_dwordx4 v[194:197], v[114:115], off
	global_load_dwordx4 v[20:23], v[116:117], off
	global_load_dwordx4 v[150:153], v[118:119], off
	global_load_dwordx4 v[162:165], v[120:121], off
	global_load_dwordx4 v[198:201], v[122:123], off
	global_load_dwordx4 v[166:169], v[126:127], off
	global_load_dwordx4 v[178:181], v[222:223], off nt
	global_load_dwordx4 v[202:205], v[222:223], off offset:64 nt
	v_lshl_add_u64 v[236:237], v[66:67], 0, v[182:183]
	global_load_dwordx4 v[24:27], v[124:125], off
	global_load_dwordx4 v[210:213], v[128:129], off
	global_load_dwordx4 v[214:217], v[130:131], off
	v_lshl_add_u64 v[182:183], v[68:69], 0, v[182:183]
	v_lshlrev_b64 v[136:137], 11, v[136:137]
	v_lshl_add_u64 v[136:137], v[134:135], 0, v[136:137]
	s_mov_b32 s33, 1
	s_waitcnt vmcnt(4)
	v_mfma_f32_16x16x32_bf16 v[206:209], v[8:11], v[178:181], 0
	v_mfma_f32_16x16x32_bf16 v[218:221], v[28:31], v[178:181], 0
	global_load_dwordx4 v[28:31], v[132:133], off
	global_load_dwordx4 v[8:11], v[72:73], off
	global_load_dwordx2 v[238:239], v[236:237], off offset:32 nt
	global_load_dwordx2 v[240:241], v[236:237], off offset:96 nt
	global_load_dwordx4 v[224:227], v[222:223], off offset:128 nt
	v_mfma_f32_16x16x32_bf16 v[52:55], v[52:55], v[178:181], 0
	global_load_dwordx2 v[242:243], v[236:237], off offset:128 nt
	global_load_dwordx2 v[244:245], v[236:237], off offset:192 nt
	v_mfma_f32_16x16x32_bf16 v[60:63], v[60:63], v[178:181], 0
	v_mfma_f32_16x16x32_bf16 v[142:145], v[142:145], v[178:181], 0
	v_mfma_f32_16x16x32_bf16 v[228:231], v[146:149], v[178:181], 0
	v_mfma_f32_16x16x32_bf16 v[232:235], v[150:153], v[178:181], 0
	v_mfma_f32_16x16x32_bf16 v[166:169], v[166:169], v[178:181], 0
	global_load_dwordx2 v[152:153], v[236:237], off offset:224 nt
	global_load_dwordx2 v[178:179], v[236:237], off nt
	global_load_dwordx2 v[246:247], v[182:183], off nt
	global_load_dwordx2 v[248:249], v[236:237], off offset:64 nt
	global_load_dwordx2 v[180:181], v[236:237], off offset:160 nt
	s_waitcnt vmcnt(15)
	v_mfma_f32_16x16x32_bf16 v[206:209], v[36:39], v[202:205], v[206:209]
	global_load_dwordx4 v[36:39], v[222:223], off offset:192 nt
	global_load_dwordx2 v[150:151], v[182:183], off offset:32 nt
	global_load_dwordx2 v[148:149], v[182:183], off offset:64 nt
	global_load_dwordx2 v[146:147], v[182:183], off offset:96 nt
	v_mfma_f32_16x16x32_bf16 v[44:47], v[44:47], v[202:205], v[218:221]
	v_mfma_f32_16x16x32_bf16 v[52:55], v[56:59], v[202:205], v[52:55]
	v_mfma_f32_16x16x32_bf16 v[56:59], v[138:141], v[202:205], v[60:63]
	v_mfma_f32_16x16x32_bf16 v[218:221], v[154:157], v[202:205], v[142:145]
	s_nop 2
	global_load_dwordx2 v[144:145], v[182:183], off offset:128 nt
	global_load_dwordx2 v[142:143], v[182:183], off offset:160 nt
	global_load_dwordx2 v[140:141], v[182:183], off offset:192 nt
	global_load_dwordx2 v[138:139], v[182:183], off offset:224 nt
	s_waitcnt vmcnt(16)
	v_lshlrev_b32_e32 v157, 16, v241
	s_waitcnt vmcnt(15)
	v_mfma_f32_16x16x32_bf16 v[60:63], v[40:43], v[224:227], v[206:209]
	v_lshlrev_b32_e32 v156, 16, v240
	s_waitcnt vmcnt(12)
	v_and_b32_e32 v155, 0xffff0000, v152
	v_mfma_f32_16x16x32_bf16 v[40:43], v[48:51], v[224:227], v[44:47]
	s_waitcnt vmcnt(9)
	v_lshlrev_b32_e32 v182, 16, v249
	v_and_b32_e32 v183, 0xffff0000, v249
	v_mfma_f32_16x16x32_bf16 v[44:47], v[170:173], v[224:227], v[52:55]
	v_lshlrev_b32_e32 v172, 16, v179
	v_and_b32_e32 v173, 0xffff0000, v179
	v_and_b32_e32 v179, 0xffff0000, v246
	v_mfma_f32_16x16x32_bf16 v[48:51], v[174:177], v[224:227], v[56:59]
	v_lshlrev_b32_e32 v176, 16, v247
	v_and_b32_e32 v177, 0xffff0000, v247
	v_lshlrev_b32_e32 v174, 16, v178
	v_mfma_f32_16x16x32_bf16 v[228:231], v[158:161], v[202:205], v[228:231]
	v_and_b32_e32 v175, 0xffff0000, v178
	v_lshlrev_b32_e32 v178, 16, v246
	v_lshlrev_b32_e32 v160, 16, v238
	s_waitcnt vmcnt(7)
; __device__ __forceinline__ float bflo(unsigned w) { return __uint_as_float(w << 16); }
; __device__ __forceinline__ float bfhi(unsigned w) { return __uint_as_float(w & 0xffff0000u); }
; #define MFMA16(a, b, c) __builtin_amdgcn_mfma_f32_16x16x32_bf16((a), (b), (c), 0, 0, 0)
; __device__ __forceinline__ void h3_unit(int j, const bf16_t* qe, const bf16_t* intra, const bf16_t* Ub, const bf16_t* hg, const float* gn, bf16_t* out) {
;     ...
;             for (int ks = 0; ks < 4; ++ks) { const bf16x8 y = *(const bf16x8*)(ub + vb * 2048 + 32 * ks); acc[vb] = MFMA16(y, x[ks], acc[vb]); } }
;         float ss = 0.f;
; #pragma unroll
;         for (int vb = 0; vb < 8; ++vb) { acc[vb][0] += bflo(iv[vb][0]); acc[vb][1] += bfhi(iv[vb][0]); acc[vb][2] += bflo(iv[vb][1]); acc[vb][3] += bfhi(iv[vb][1]);
;             ss += (acc[vb][0] * acc[vb][0] + acc[vb][1] * acc[vb][1]) + (acc[vb][2] * acc[vb][2] + acc[vb][3] * acc[vb][3]); }
;         ss += __shfl_xor(ss, 16); ss += __shfl_xor(ss, 32);
;         const float rstd = rsqrtf(ss * (1.f / 128.f) + 1e-6f);
; #pragma unroll
;         for (int vb = 0; vb < 8; ++vb) { const f32x4 gnv = *(const f32x4*)(gn + 16 * vb + 4 * l4);
	v_mfma_f32_16x16x32_bf16 v[32:35], v[32:35], v[36:39], v[60:63]
	v_and_b32_e32 v161, 0xffff0000, v238
	v_lshlrev_b32_e32 v170, 16, v245
	v_and_b32_e32 v171, 0xffff0000, v245
	v_lshlrev_b32_e32 v60, 16, v153
	v_and_b32_e32 v61, 0xffff0000, v153
	v_mfma_f32_16x16x32_bf16 v[0:3], v[0:3], v[36:39], v[40:43]
	v_mul_f32_e32 v62, 0xbfb8aa3b, v178
	v_mul_f32_e32 v63, 0xbfb8aa3b, v179
	v_mul_f32_e32 v153, 0xbfb8aa3b, v176
	v_mfma_f32_16x16x32_bf16 v[40:43], v[4:7], v[36:39], v[44:47]
	v_mul_f32_e32 v4, 0xbfb8aa3b, v177
	v_exp_f32_e32 v5, v62
	v_exp_f32_e32 v62, v63
	v_mfma_f32_16x16x32_bf16 v[44:47], v[12:15], v[36:39], v[48:51]
	v_exp_f32_e32 v12, v153
	v_exp_f32_e32 v13, v4
	v_add_f32_e32 v14, 1.0, v5
	v_mfma_f32_16x16x32_bf16 v[232:235], v[162:165], v[202:205], v[232:235]
	v_add_f32_e32 v15, 1.0, v62
	v_add_f32_e32 v12, 1.0, v12
	v_add_f32_e32 v48, 1.0, v13
	v_mfma_f32_16x16x32_bf16 v[202:205], v[210:213], v[202:205], v[166:169]
	v_lshlrev_b32_e32 v162, 16, v239
	v_and_b32_e32 v163, 0xffff0000, v239
	v_lshlrev_b32_e32 v164, 16, v242
	v_mfma_f32_16x16x32_bf16 v[52:55], v[190:193], v[224:227], v[218:221]
	v_and_b32_e32 v165, 0xffff0000, v242
	v_lshlrev_b32_e32 v166, 16, v243
	v_and_b32_e32 v167, 0xffff0000, v243
	v_mfma_f32_16x16x32_bf16 v[56:59], v[194:197], v[224:227], v[228:231]
	v_add_f32_e64 v34, v34, v172
	v_add_f32_e64 v35, v35, v173
	v_lshlrev_b32_e32 v168, 16, v244
	v_and_b32_e32 v169, 0xffff0000, v244
	v_mfma_f32_16x16x32_bf16 v[190:193], v[198:201], v[224:227], v[232:235]
	v_lshlrev_b32_e32 v198, 16, v248
	v_and_b32_e32 v199, 0xffff0000, v248
	v_lshlrev_b32_e32 v200, 16, v181
	v_mfma_f32_16x16x32_bf16 v[194:197], v[214:217], v[224:227], v[202:205]
	v_and_b32_e32 v201, 0xffff0000, v181
	v_pk_add_f32 v[32:33], v[32:33], v[174:175]
	v_pk_add_f32 v[40:41], v[40:41], v[198:199]
	v_mfma_f32_16x16x32_bf16 v[4:7], v[16:19], v[36:39], v[52:55]
	v_lshlrev_b32_e32 v202, 16, v180
	v_and_b32_e32 v203, 0xffff0000, v180
	v_pk_mul_f32 v[50:51], v[34:35], v[34:35]
	v_mfma_f32_16x16x32_bf16 v[16:19], v[20:23], v[36:39], v[56:59]
	v_rcp_f32_e32 v20, v14
	v_rcp_f32_e32 v21, v15
	v_rcp_f32_e32 v22, v12
	v_rcp_f32_e32 v23, v48
	v_mfma_f32_16x16x32_bf16 v[12:15], v[24:27], v[36:39], v[190:193]
	v_mul_f32_e64 v24, v20, v178
	v_mul_f32_e64 v25, v21, v179
	v_and_b32_e32 v159, 0xffff0000, v241
	v_pk_mul_f32 v[26:27], v[22:23], v[176:177]
	v_mfma_f32_16x16x32_bf16 v[20:23], v[28:31], v[36:39], v[194:197]
	v_add_f32_e64 v28, v0, v160
	v_add_f32_e64 v29, v1, v161
	v_pk_add_f32 v[30:31], v[2:3], v[162:163]
	v_mov_b32_e32 v2, v44
	v_mov_b32_e32 v3, v46
	v_pk_add_f32 v[36:37], v[4:5], v[164:165]
	v_pk_add_f32 v[38:39], v[6:7], v[166:167]
	v_and_b32_e32 v158, 0xffff0000, v240
	v_mov_b32_e32 v46, v45
	v_pk_add_f32 v[12:13], v[12:13], v[168:169]
	v_pk_add_f32 v[6:7], v[14:15], v[170:171]
	v_pk_add_f32 v[42:43], v[42:43], v[182:183]
	v_pk_add_f32 v[14:15], v[18:19], v[200:201]
	v_pk_add_f32 v[16:17], v[16:17], v[202:203]
	v_mov_b32_e32 v5, v21
	v_pk_add_f32 v[0:1], v[22:23], v[60:61]
	v_mul_f32_e32 v4, v29, v29
	v_mul_f32_e32 v18, v31, v31
	v_pk_add_f32 v[22:23], v[2:3], v[156:157]
	v_mul_f32_e32 v2, v37, v37
	v_pk_mul_f32 v[52:53], v[32:33], v[32:33]
	v_mul_f32_e32 v50, v39, v39
	v_mov_b32_e32 v3, v41
	v_pk_add_f32 v[44:45], v[46:47], v[158:159]
	v_mul_f32_e32 v46, v13, v13
	v_mul_f32_e32 v48, v7, v7
	v_pk_mul_f32 v[54:55], v[42:43], v[42:43]
	v_pk_mul_f32 v[60:61], v[16:17], v[16:17]
	v_pk_fma_f32 v[156:157], v[28:29], v[28:29], v[4:5] op_sel_hi:[1,1,0]
	v_pk_fma_f32 v[18:19], v[30:31], v[30:31], v[18:19] op_sel_hi:[1,1,0]
	v_pk_fma_f32 v[160:161], v[36:37], v[36:37], v[2:3] op_sel_hi:[1,1,0]
	v_pk_fma_f32 v[162:163], v[38:39], v[38:39], v[50:51] op_sel_hi:[1,1,0]
	v_mov_b32_e32 v2, v51
	v_pk_mov_b32 v[50:51], v[52:53], v[40:41] op_sel:[1,0]
	v_pk_mul_f32 v[56:57], v[40:41], v[40:41]
	v_pk_mul_f32 v[62:63], v[0:1], v[0:1]
	v_pk_fma_f32 v[46:47], v[12:13], v[12:13], v[46:47] op_sel_hi:[1,1,0]
	v_pk_fma_f32 v[48:49], v[6:7], v[6:7], v[48:49] op_sel_hi:[1,1,0]
	v_mov_b32_e32 v4, v60
	v_mov_b32_e32 v154, v61
	v_mov_b32_e32 v157, v54
	v_mov_b32_e32 v19, v55
	v_pk_fma_f32 v[54:55], v[34:35], v[34:35], v[2:3]
	v_pk_fma_f32 v[60:61], v[32:33], v[32:33], v[50:51]
	v_pk_mul_f32 v[50:51], v[40:41], v[50:51] op_sel_hi:[0,1]
	v_pk_mul_f32 v[158:159], v[44:45], v[44:45]
	v_mov_b32_e32 v47, v62
	v_mov_b32_e32 v49, v63
	v_mov_b32_e32 v55, v57
	v_mov_b32_e32 v61, v51
	v_pk_fma_f32 v[52:53], v[22:23], v[22:23], v[158:159]
	v_pk_add_f32 v[18:19], v[156:157], v[18:19]
	v_pk_add_f32 v[46:47], v[46:47], v[48:49]
	v_pk_add_f32 v[48:49], v[60:61], v[54:55]
	v_pk_add_f32 v[2:3], v[4:5], v[154:155]
	v_pk_add_f32 v[4:5], v[52:53], v[52:53] op_sel:[0,1] op_sel_hi:[1,0]
	v_pk_add_f32 v[18:19], v[48:49], v[18:19]
	v_pk_mul_f32 v[58:59], v[14:15], v[14:15]
	v_lshlrev_b32_e32 v5, 16, v152
	v_pk_add_f32 v[18:19], v[18:19], v[18:19] op_sel:[0,1] op_sel_hi:[1,0]
	v_mov_b32_e32 v161, v20
	v_mov_b32_e32 v154, v59
	v_mov_b32_e32 v163, v5
	v_mov_b32_e32 v19, v20
	v_mov_b32_e32 v20, v58
	v_pk_add_f32 v[48:49], v[160:161], v[162:163]
	v_pk_add_f32 v[4:5], v[18:19], v[4:5]
	v_pk_add_f32 v[18:19], v[20:21], v[154:155]
	v_pk_add_f32 v[20:21], v[4:5], v[48:49]
	v_pk_mul_f32 v[48:49], v[4:5], v[48:49]
	v_pk_add_f32 v[50:51], v[2:3], v[18:19]
	v_pk_mul_f32 v[18:19], v[2:3], v[18:19]
	v_mov_b32_e32 v21, v49
	v_mov_b32_e32 v51, v19
	v_pk_add_f32 v[18:19], v[20:21], v[50:51]
	global_load_dwordx4 v[48:51], v[72:73], off offset:64
	global_load_dwordx4 v[52:55], v[72:73], off offset:128
	global_load_dwordx4 v[56:59], v[72:73], off offset:192
	global_load_dwordx4 v[60:63], v[72:73], off offset:256
	global_load_dwordx4 v[152:155], v[72:73], off offset:320
	global_load_dwordx4 v[156:159], v[72:73], off offset:384
	global_load_dwordx4 v[160:163], v[72:73], off offset:448
	s_nop 0
	v_pk_add_f32 v[18:19], v[18:19], v[46:47]
	s_nop 0
	v_add_f32_e32 v2, v18, v19
	ds_bpermute_b32 v4, v186, v2
	s_waitcnt lgkmcnt(0)
; __device__ __forceinline__ float bflo(unsigned w) { return __uint_as_float(w << 16); }
; __device__ __forceinline__ float bfhi(unsigned w) { return __uint_as_float(w & 0xffff0000u); }
; __device__ __forceinline__ unsigned pk2(float lo, float hi) { f32x2_t v = {lo, hi}; bf16x2_t b = __builtin_convertvector(v, bf16x2_t); return __builtin_bit_cast(unsigned, b); }
; __device__ __forceinline__ float sigmoidf_(float x) { return __builtin_amdgcn_rcpf(1.0f + __expf(-x)); }
; __device__ __forceinline__ void h3_unit(int j, const bf16_t* qe, const bf16_t* intra, const bf16_t* Ub, const bf16_t* hg, const float* gn, bf16_t* out) {
;     ...
;         ss += __shfl_xor(ss, 16); ss += __shfl_xor(ss, 32);
;         const float rstd = rsqrtf(ss * (1.f / 128.f) + 1e-6f);
; #pragma unroll
;         for (int vb = 0; vb < 8; ++vb) { const f32x4 gnv = *(const f32x4*)(gn + 16 * vb + 4 * l4);
;             const float g0 = bflo(gv[vb][0]), g1 = bfhi(gv[vb][0]), g2 = bflo(gv[vb][1]), g3 = bfhi(gv[vb][1]);
;             u32x2 w; w[0] = pk2(acc[vb][0] * rstd * gnv[0] * (g0 * sigmoidf_(g0)), acc[vb][1] * rstd * gnv[1] * (g1 * sigmoidf_(g1)));
;             w[1] = pk2(acc[vb][2] * rstd * gnv[2] * (g2 * sigmoidf_(g2)), acc[vb][3] * rstd * gnv[3] * (g3 * sigmoidf_(g3)));
;             *(u32x2*)(out + (size_t)(t0 + 16 * tb + l15) * 1024 + 512 + head * 128 + 16 * vb + 4 * l4) = w; }
	v_add_f32_e32 v2, v2, v4
	ds_bpermute_b32 v4, v187, v2
	s_waitcnt lgkmcnt(0)
	v_add_f32_e32 v2, v2, v4
	v_fmamk_f32 v2, v2, 0x3c000000, v185
	v_mul_f32_e32 v4, 0x4b800000, v2
	v_cmp_gt_f32_e32 vcc, s3, v2
	s_nop 1
	v_cndmask_b32_e32 v2, v2, v4, vcc
	v_rsq_f32_e32 v2, v2
	s_nop 0
	v_mul_f32_e32 v4, 0x45800000, v2
	v_cndmask_b32_e32 v4, v2, v4, vcc
	v_pk_mul_f32 v[18:19], v[32:33], v[4:5] op_sel_hi:[1,0]
	v_pk_mul_f32 v[20:21], v[34:35], v[4:5] op_sel_hi:[1,0]
	v_pk_mul_f32 v[8:9], v[8:9], v[18:19]
	v_pk_mul_f32 v[10:11], v[10:11], v[20:21]
	v_pk_mul_f32 v[8:9], v[24:25], v[8:9]
	v_pk_mul_f32 v[10:11], v[26:27], v[10:11]
	v_cvt_pk_bf16_f32 v8, v8, v9
	v_cvt_pk_bf16_f32 v9, v10, v11
	global_store_dwordx2 v[136:137], v[8:9], off offset:1024
	s_waitcnt vmcnt(14)
	v_lshlrev_b32_e32 v18, 16, v150
	v_and_b32_e32 v19, 0xffff0000, v150
	v_lshlrev_b32_e32 v20, 16, v151
	v_and_b32_e32 v21, 0xffff0000, v151
	v_mul_f32_e32 v2, 0xbfb8aa3b, v18
	v_mul_f32_e32 v24, 0xbfb8aa3b, v19
	v_mul_f32_e32 v25, 0xbfb8aa3b, v20
	v_mul_f32_e32 v26, 0xbfb8aa3b, v21
	v_exp_f32_e32 v2, v2
	v_exp_f32_e32 v24, v24
	v_exp_f32_e32 v25, v25
	v_exp_f32_e32 v26, v26
	v_add_f32_e32 v2, 1.0, v2
	v_add_f32_e32 v27, 1.0, v24
	v_add_f32_e32 v32, 1.0, v25
	v_add_f32_e32 v33, 1.0, v26
	v_rcp_f32_e32 v24, v2
	v_rcp_f32_e32 v25, v27
	v_rcp_f32_e32 v26, v32
	v_rcp_f32_e32 v27, v33
	v_pk_mul_f32 v[16:17], v[16:17], v[4:5] op_sel_hi:[1,0]
	v_pk_mul_f32 v[18:19], v[24:25], v[18:19]
	v_pk_mul_f32 v[24:25], v[28:29], v[4:5] op_sel_hi:[1,0]
	v_pk_mul_f32 v[20:21], v[26:27], v[20:21]
	v_pk_mul_f32 v[26:27], v[30:31], v[4:5] op_sel_hi:[1,0]
	v_pk_mul_f32 v[14:15], v[14:15], v[4:5] op_sel_hi:[1,0]
	v_pk_mul_f32 v[12:13], v[12:13], v[4:5] op_sel_hi:[1,0]
	v_pk_mul_f32 v[6:7], v[6:7], v[4:5] op_sel_hi:[1,0]
	v_pk_mul_f32 v[0:1], v[0:1], v[4:5] op_sel_hi:[1,0]
	s_and_b64 vcc, exec, s[80:81]
	s_mov_b64 s[80:81], 0
	s_waitcnt vmcnt(7)
	v_pk_mul_f32 v[8:9], v[48:49], v[24:25]
	v_pk_mul_f32 v[10:11], v[50:51], v[26:27]
	v_pk_mul_f32 v[8:9], v[18:19], v[8:9]
	v_pk_mul_f32 v[10:11], v[20:21], v[10:11]
	v_cvt_pk_bf16_f32 v8, v8, v9
	v_cvt_pk_bf16_f32 v9, v10, v11
	global_store_dwordx2 v[136:137], v[8:9], off offset:1056
	v_lshlrev_b32_e32 v18, 16, v149
	v_and_b32_e32 v19, 0xffff0000, v149
	v_lshlrev_b32_e32 v20, 16, v148
	v_and_b32_e32 v21, 0xffff0000, v148
	v_mul_f32_e32 v2, 0xbfb8aa3b, v20
	v_mul_f32_e32 v24, 0xbfb8aa3b, v21
	v_mul_f32_e32 v25, 0xbfb8aa3b, v18
	v_mul_f32_e32 v26, 0xbfb8aa3b, v19
	v_exp_f32_e32 v2, v2
	v_exp_f32_e32 v24, v24
	v_exp_f32_e32 v25, v25
	v_exp_f32_e32 v26, v26
	v_add_f32_e32 v2, 1.0, v2
	v_add_f32_e32 v27, 1.0, v24
	v_add_f32_e32 v28, 1.0, v25
	v_add_f32_e32 v29, 1.0, v26
	v_rcp_f32_e32 v24, v2
	v_rcp_f32_e32 v25, v27
	v_rcp_f32_e32 v26, v28
	v_rcp_f32_e32 v27, v29
	v_pk_mul_f32 v[20:21], v[24:25], v[20:21]
	v_pk_mul_f32 v[24:25], v[40:41], v[4:5] op_sel_hi:[1,0]
	v_pk_mul_f32 v[18:19], v[26:27], v[18:19]
	v_pk_mul_f32 v[26:27], v[42:43], v[4:5] op_sel_hi:[1,0]
	s_waitcnt vmcnt(7)
	v_pk_mul_f32 v[8:9], v[52:53], v[24:25]
	v_pk_mul_f32 v[10:11], v[54:55], v[26:27]
	v_pk_mul_f32 v[8:9], v[20:21], v[8:9]
	v_pk_mul_f32 v[10:11], v[18:19], v[10:11]
	v_cvt_pk_bf16_f32 v8, v8, v9
	v_cvt_pk_bf16_f32 v9, v10, v11
	global_store_dwordx2 v[136:137], v[8:9], off offset:1088
	v_lshlrev_b32_e32 v18, 16, v146
	v_and_b32_e32 v19, 0xffff0000, v146
	v_lshlrev_b32_e32 v20, 16, v147
	v_mul_f32_e32 v2, 0xbfb8aa3b, v18
	v_mul_f32_e32 v24, 0xbfb8aa3b, v19
	v_and_b32_e32 v21, 0xffff0000, v147
	v_mul_f32_e32 v25, 0xbfb8aa3b, v20
	v_exp_f32_e32 v2, v2
	v_exp_f32_e32 v24, v24
	v_mul_f32_e32 v26, 0xbfb8aa3b, v21
	v_exp_f32_e32 v25, v25
	v_exp_f32_e32 v26, v26
	v_add_f32_e32 v2, 1.0, v2
	v_add_f32_e32 v27, 1.0, v24
	v_add_f32_e32 v28, 1.0, v25
	v_rcp_f32_e32 v24, v2
	v_rcp_f32_e32 v25, v27
	v_add_f32_e32 v29, 1.0, v26
	v_rcp_f32_e32 v26, v28
	v_rcp_f32_e32 v27, v29
	v_pk_mul_f32 v[18:19], v[24:25], v[18:19]
	v_mov_b32_e32 v24, v22
	v_mov_b32_e32 v25, v44
	v_mov_b32_e32 v44, v23
	v_pk_mul_f32 v[22:23], v[24:25], v[4:5] op_sel_hi:[1,0]
	v_pk_mul_f32 v[24:25], v[44:45], v[4:5] op_sel_hi:[1,0]
	v_pk_mul_f32 v[20:21], v[26:27], v[20:21]
	s_waitcnt vmcnt(7)
; __device__ __forceinline__ float bflo(unsigned w) { return __uint_as_float(w << 16); }
; __device__ __forceinline__ float bfhi(unsigned w) { return __uint_as_float(w & 0xffff0000u); }
; __device__ __forceinline__ unsigned pk2(float lo, float hi) { f32x2_t v = {lo, hi}; bf16x2_t b = __builtin_convertvector(v, bf16x2_t); return __builtin_bit_cast(unsigned, b); }
; __device__ __forceinline__ float sigmoidf_(float x) { return __builtin_amdgcn_rcpf(1.0f + __expf(-x)); }
; __device__ __forceinline__ void h3_unit(int j, const bf16_t* qe, const bf16_t* intra, const bf16_t* Ub, const bf16_t* hg, const float* gn, bf16_t* out) {
;     ...
;         for (int vb = 0; vb < 8; ++vb) { const f32x4 gnv = *(const f32x4*)(gn + 16 * vb + 4 * l4);
;             const float g0 = bflo(gv[vb][0]), g1 = bfhi(gv[vb][0]), g2 = bflo(gv[vb][1]), g3 = bfhi(gv[vb][1]);
;             u32x2 w; w[0] = pk2(acc[vb][0] * rstd * gnv[0] * (g0 * sigmoidf_(g0)), acc[vb][1] * rstd * gnv[1] * (g1 * sigmoidf_(g1)));
;             w[1] = pk2(acc[vb][2] * rstd * gnv[2] * (g2 * sigmoidf_(g2)), acc[vb][3] * rstd * gnv[3] * (g3 * sigmoidf_(g3)));
;             *(u32x2*)(out + (size_t)(t0 + 16 * tb + l15) * 1024 + 512 + head * 128 + 16 * vb + 4 * l4) = w; }
	v_pk_mul_f32 v[8:9], v[56:57], v[22:23]
	v_pk_mul_f32 v[10:11], v[58:59], v[24:25]
	v_pk_mul_f32 v[8:9], v[18:19], v[8:9]
	v_pk_mul_f32 v[10:11], v[20:21], v[10:11]
	v_cvt_pk_bf16_f32 v8, v8, v9
	v_cvt_pk_bf16_f32 v9, v10, v11
	global_store_dwordx2 v[136:137], v[8:9], off offset:1120
	v_lshlrev_b32_e32 v18, 16, v144
	v_and_b32_e32 v19, 0xffff0000, v144
	v_lshlrev_b32_e32 v20, 16, v145
	v_and_b32_e32 v21, 0xffff0000, v145
	v_mul_f32_e32 v2, 0xbfb8aa3b, v18
	v_mul_f32_e32 v22, 0xbfb8aa3b, v19
	v_mul_f32_e32 v23, 0xbfb8aa3b, v20
	v_mul_f32_e32 v24, 0xbfb8aa3b, v21
	v_exp_f32_e32 v2, v2
	v_exp_f32_e32 v22, v22
	v_exp_f32_e32 v23, v23
	v_exp_f32_e32 v24, v24
	v_add_f32_e32 v2, 1.0, v2
	v_add_f32_e32 v25, 1.0, v22
	v_add_f32_e32 v26, 1.0, v23
	v_add_f32_e32 v27, 1.0, v24
	v_rcp_f32_e32 v22, v2
	v_rcp_f32_e32 v23, v25
	v_rcp_f32_e32 v24, v26
	v_rcp_f32_e32 v25, v27
	v_pk_mul_f32 v[18:19], v[22:23], v[18:19]
	v_pk_mul_f32 v[22:23], v[36:37], v[4:5] op_sel_hi:[1,0]
	v_pk_mul_f32 v[20:21], v[24:25], v[20:21]
	v_pk_mul_f32 v[24:25], v[38:39], v[4:5] op_sel_hi:[1,0]
	s_waitcnt vmcnt(7)
	v_pk_mul_f32 v[8:9], v[60:61], v[22:23]
	v_pk_mul_f32 v[10:11], v[62:63], v[24:25]
	v_pk_mul_f32 v[8:9], v[18:19], v[8:9]
	v_pk_mul_f32 v[10:11], v[20:21], v[10:11]
	v_cvt_pk_bf16_f32 v8, v8, v9
	v_cvt_pk_bf16_f32 v9, v10, v11
	global_store_dwordx2 v[136:137], v[8:9], off offset:1152
	v_lshlrev_b32_e32 v18, 16, v143
	v_and_b32_e32 v19, 0xffff0000, v143
	v_lshlrev_b32_e32 v20, 16, v142
	v_and_b32_e32 v21, 0xffff0000, v142
	v_mul_f32_e32 v2, 0xbfb8aa3b, v20
	v_mul_f32_e32 v22, 0xbfb8aa3b, v21
	v_mul_f32_e32 v23, 0xbfb8aa3b, v18
	v_mul_f32_e32 v24, 0xbfb8aa3b, v19
	v_exp_f32_e32 v2, v2
	v_exp_f32_e32 v22, v22
	v_exp_f32_e32 v23, v23
	v_exp_f32_e32 v24, v24
	v_add_f32_e32 v2, 1.0, v2
	v_add_f32_e32 v25, 1.0, v22
	v_add_f32_e32 v26, 1.0, v23
	v_add_f32_e32 v27, 1.0, v24
	v_rcp_f32_e32 v22, v2
	v_rcp_f32_e32 v23, v25
	v_rcp_f32_e32 v24, v26
	v_rcp_f32_e32 v25, v27
	v_pk_mul_f32 v[20:21], v[22:23], v[20:21]
	v_pk_mul_f32 v[18:19], v[24:25], v[18:19]
	s_waitcnt vmcnt(7)
	v_pk_mul_f32 v[8:9], v[152:153], v[16:17]
	v_pk_mul_f32 v[10:11], v[154:155], v[14:15]
	v_pk_mul_f32 v[8:9], v[20:21], v[8:9]
	v_pk_mul_f32 v[10:11], v[18:19], v[10:11]
	v_cvt_pk_bf16_f32 v8, v8, v9
	v_cvt_pk_bf16_f32 v9, v10, v11
	global_store_dwordx2 v[136:137], v[8:9], off offset:1184
	v_lshlrev_b32_e32 v14, 16, v140
	v_and_b32_e32 v15, 0xffff0000, v140
	v_lshlrev_b32_e32 v16, 16, v141
	v_and_b32_e32 v17, 0xffff0000, v141
	v_mul_f32_e32 v2, 0xbfb8aa3b, v14
	v_mul_f32_e32 v18, 0xbfb8aa3b, v15
	v_mul_f32_e32 v19, 0xbfb8aa3b, v16
	v_mul_f32_e32 v20, 0xbfb8aa3b, v17
	v_exp_f32_e32 v2, v2
	v_exp_f32_e32 v18, v18
	v_exp_f32_e32 v19, v19
	v_exp_f32_e32 v20, v20
	v_add_f32_e32 v2, 1.0, v2
	v_add_f32_e32 v21, 1.0, v18
	v_add_f32_e32 v22, 1.0, v19
	v_add_f32_e32 v23, 1.0, v20
	v_rcp_f32_e32 v18, v2
	v_rcp_f32_e32 v19, v21
	v_rcp_f32_e32 v20, v22
	v_rcp_f32_e32 v21, v23
	v_pk_mul_f32 v[14:15], v[18:19], v[14:15]
	v_pk_mul_f32 v[16:17], v[20:21], v[16:17]
	s_waitcnt vmcnt(7)
	v_pk_mul_f32 v[8:9], v[156:157], v[12:13]
	v_pk_mul_f32 v[6:7], v[158:159], v[6:7]
	v_pk_mul_f32 v[8:9], v[14:15], v[8:9]
	v_pk_mul_f32 v[6:7], v[16:17], v[6:7]
	v_cvt_pk_bf16_f32 v8, v8, v9
	v_cvt_pk_bf16_f32 v9, v6, v7
	global_store_dwordx2 v[136:137], v[8:9], off offset:1216
	v_lshlrev_b32_e32 v10, 16, v139
	v_and_b32_e32 v11, 0xffff0000, v139
	v_lshlrev_b32_e32 v12, 16, v138
	v_and_b32_e32 v13, 0xffff0000, v138
	v_mul_f32_e32 v2, 0xbfb8aa3b, v12
	v_mul_f32_e32 v14, 0xbfb8aa3b, v13
	v_mul_f32_e32 v15, 0xbfb8aa3b, v10
	v_mul_f32_e32 v16, 0xbfb8aa3b, v11
	v_exp_f32_e32 v2, v2
	v_exp_f32_e32 v14, v14
	v_exp_f32_e32 v15, v15
	v_exp_f32_e32 v16, v16
	v_add_f32_e32 v2, 1.0, v2
	v_add_f32_e32 v17, 1.0, v14
	v_add_f32_e32 v18, 1.0, v15
	v_add_f32_e32 v19, 1.0, v16
	v_rcp_f32_e32 v14, v2
	v_rcp_f32_e32 v15, v17
	v_rcp_f32_e32 v16, v18
	v_rcp_f32_e32 v17, v19
	v_mov_b32_e32 v2, v5
	v_pk_mul_f32 v[2:3], v[2:3], v[4:5] op_sel_hi:[1,0]
	v_pk_mul_f32 v[12:13], v[14:15], v[12:13]
	v_pk_mul_f32 v[10:11], v[16:17], v[10:11]
	s_waitcnt vmcnt(7)
	v_pk_mul_f32 v[2:3], v[2:3], v[160:161]
	v_pk_mul_f32 v[0:1], v[0:1], v[162:163]
	v_pk_mul_f32 v[2:3], v[12:13], v[2:3]
	v_pk_mul_f32 v[0:1], v[10:11], v[0:1]
	v_cvt_pk_bf16_f32 v2, v2, v3
	v_cvt_pk_bf16_f32 v3, v0, v1
	global_store_dwordx2 v[136:137], v[2:3], off offset:1248
	s_cbranch_vccnz .LBB0_836
	s_add_i32 s28, s28, s86
	s_cmpk_gt_i32 s28, 0x1ff
	s_cbranch_scc0 .LBB0_835
